# v59 + MLA loop: V-tile DMAs issued at the end of each half (head block issues K,K,rope-K only), tile barriers wait vmcnt(2), loop exit drains
# baseline (speedup 1.0000x reference)
.LBB0_543:
	s_mov_b32 s23, s17
	s_mov_b32 s17, s0
	s_add_i32 s71, 0, 0x10000
	ds_read_b128 v[66:69], v174 offset:49152
	ds_read_b128 v[70:73], v174 offset:57344
	ds_read_b128 v[206:209], v176 offset:49152
	ds_read_b128 v[210:213], v176 offset:57344
	s_add_u32 s4, s38, s20
	s_addc_u32 s5, s39, s21
	s_add_u32 s24, s4, 0x149ec400
	s_addc_u32 s25, s5, 0
	s_mov_b32 m0, s90
	v_lshl_add_u64 v[254:255], v[246:247], 0, s[24:25]
	s_lshl_b32 s18, s22, 14
	global_load_lds_dwordx4 v[254:255], off
	s_add_u32 s24, s4, 0x14a0c400
	s_addc_u32 s25, s5, 0
	s_mov_b32 m0, s91
	v_lshl_add_u64 v[254:255], v[246:247], 0, s[24:25]
	s_add_i32 s1, s89, s18
	global_load_lds_dwordx4 v[254:255], off
	s_add_u32 s24, s38, s88
	s_addc_u32 s25, s39, s87
	s_add_u32 s24, s24, s36
	s_addc_u32 s25, s25, s37
	s_mov_b32 m0, s92
	v_lshl_add_u64 v[254:255], v[250:251], 0, s[24:25]
	global_load_lds_dwordx4 v[254:255], off
	v_fma_f32 v152, v74, s34, v146
	v_fma_f32 v153, v75, s34, v146
	v_fma_f32 v150, v76, s34, v146
	v_fma_f32 v151, v77, s34, v146
	v_fma_f32 v148, v78, s34, v146
	v_fma_f32 v149, v79, s34, v146
	v_fma_f32 v147, v81, s34, v146
	v_fma_f32 v146, v80, s34, v146
	v_exp_f32_e32 v229, v229
	v_exp_f32_e32 v231, v231
	v_exp_f32_e32 v227, v227
	v_exp_f32_e32 v230, v230
	v_exp_f32_e32 v226, v226
	v_exp_f32_e32 v228, v228
	s_waitcnt lgkmcnt(0)
	v_mfma_f32_32x32x16_bf16 v[82:97], v[66:69], v[142:145], 0
	s_add_i32 s0, 0, 0x16000
	v_exp_f32_e32 v240, v146
	v_add_f32_e32 v146, 0, v229
	v_add_f32_e32 v146, v231, v146
	v_add_f32_e32 v146, v227, v146
	v_add_f32_e32 v146, v230, v146
	v_add_f32_e32 v146, v226, v146
	v_exp_f32_e32 v224, v224
	v_exp_f32_e32 v225, v225
	v_exp_f32_e32 v221, v221
	v_exp_f32_e32 v223, v223
	v_mfma_f32_32x32x16_bf16 v[66:81], v[70:73], v[142:145], 0
	v_exp_f32_e32 v220, v220
	v_exp_f32_e32 v222, v222
	v_add_f32_e32 v146, v228, v146
	v_add_f32_e32 v146, v224, v146
	v_add_f32_e32 v146, v225, v146
	v_add_f32_e32 v146, v221, v146
	v_add_f32_e32 v146, v223, v146
	v_add_f32_e32 v146, v220, v146
	v_add_f32_e32 v146, v222, v146
	v_exp_f32_e32 v217, v217
	v_exp_f32_e32 v219, v219
	v_exp_f32_e32 v216, v216
	v_exp_f32_e32 v218, v218
	v_mfma_f32_32x32x16_bf16 v[82:97], v[206:209], v[138:141], v[82:97]
	v_exp_f32_e32 v164, v164
	v_add_f32_e32 v146, v217, v146
	v_exp_f32_e32 v165, v165
	v_add_f32_e32 v146, v219, v146
	v_exp_f32_e32 v197, v162
	v_add_f32_e32 v146, v216, v146
	v_add_f32_e32 v146, v218, v146
	v_mfma_f32_32x32x16_bf16 v[66:81], v[210:213], v[138:141], v[66:81]
	ds_read_b128 v[206:209], v178 offset:49152
	ds_read_b128 v[210:213], v178 offset:57344
	v_exp_f32_e32 v156, v156
	v_add_f32_e32 v146, v164, v146
	v_exp_f32_e32 v157, v157
	v_add_f32_e32 v146, v165, v146
	v_add_f32_e32 v146, v197, v146
	v_exp_f32_e32 v241, v147
	s_waitcnt lgkmcnt(0)
	v_mfma_f32_32x32x16_bf16 v[82:97], v[206:209], v[134:137], v[82:97]
	v_mfma_f32_32x32x16_bf16 v[66:81], v[210:213], v[134:137], v[66:81]
	ds_read_b128 v[208:211], v180 offset:49152
	ds_read_b128 v[212:215], v180 offset:57344
	s_waitcnt lgkmcnt(0)
	v_mfma_f32_32x32x16_bf16 v[82:97], v[208:211], v[130:133], v[82:97]
	v_mfma_f32_32x32x16_bf16 v[66:81], v[212:215], v[130:133], v[66:81]
	ds_read_b128 v[208:211], v182 offset:49152
	ds_read_b128 v[212:215], v182 offset:57344
	s_waitcnt lgkmcnt(0)
	v_mfma_f32_32x32x16_bf16 v[82:97], v[208:211], v[126:129], v[82:97]
	v_mfma_f32_32x32x16_bf16 v[66:81], v[212:215], v[126:129], v[66:81]
	ds_read_b128 v[210:213], v186 offset:49152
	ds_read_b128 v[232:235], v186 offset:57344
	s_waitcnt lgkmcnt(0)
	v_mfma_f32_32x32x16_bf16 v[82:97], v[210:213], v[122:125], v[82:97]
	v_mfma_f32_32x32x16_bf16 v[66:81], v[232:235], v[122:125], v[66:81]
	ds_read_b128 v[210:213], v188 offset:49152
	ds_read_b128 v[232:235], v188 offset:57344
	s_waitcnt lgkmcnt(0)
	v_mfma_f32_32x32x16_bf16 v[82:97], v[210:213], v[118:121], v[82:97]
	v_mfma_f32_32x32x16_bf16 v[66:81], v[232:235], v[118:121], v[66:81]
	ds_read_b128 v[212:215], v190 offset:49152
	ds_read_b128 v[232:235], v190 offset:57344
	s_waitcnt lgkmcnt(0)
	v_mfma_f32_32x32x16_bf16 v[82:97], v[212:215], v[114:117], v[82:97]
	v_mfma_f32_32x32x16_bf16 v[66:81], v[232:235], v[114:117], v[66:81]
	ds_read_b128 v[212:215], v192 offset:8192
	ds_read_b128 v[232:235], v192 offset:12288
	s_waitcnt lgkmcnt(0)
	v_mfma_f32_32x32x16_bf16 v[82:97], v[212:215], v[110:113], v[82:97]
	v_exp_f32_e32 v215, v163
	s_nop 0
	v_add_f32_e32 v146, v215, v146
	v_mfma_f32_32x32x16_bf16 v[66:81], v[232:235], v[110:113], v[66:81]
	s_lshl_b32 s24, s17, 14
	v_add_u32_e32 v245, s24, v200
	ds_read_b64_tr_b16 v[206:207], v245 offset:0
	ds_read_b64_tr_b16 v[208:209], v245 offset:0x800
	ds_read_b64_tr_b16 v[210:211], v245 offset:0x1000
	ds_read_b64_tr_b16 v[212:213], v245 offset:0x1800
	ds_read_b128 v[232:235], v194 offset:8192
	ds_read_b128 v[236:239], v194 offset:12288
	v_add_f32_e32 v146, v156, v146
	v_add_f32_e32 v146, v157, v146
	s_waitcnt lgkmcnt(0)
	v_mfma_f32_32x32x16_bf16 v[82:97], v[232:235], v[106:109], v[82:97]
	v_mfma_f32_32x32x16_bf16 v[66:81], v[236:239], v[106:109], v[66:81]
	ds_read_b128 v[232:235], v196 offset:8192
	ds_read_b128 v[236:239], v196 offset:12288
	s_waitcnt lgkmcnt(0)
	v_mfma_f32_32x32x16_bf16 v[82:97], v[232:235], v[102:105], v[82:97]
	v_mfma_f32_32x32x16_bf16 v[66:81], v[236:239], v[102:105], v[66:81]
	ds_read_b128 v[232:235], v199 offset:8192
	ds_read_b128 v[236:239], v199 offset:12288
	s_waitcnt lgkmcnt(0)
	v_mfma_f32_32x32x16_bf16 v[82:97], v[232:235], v[98:101], v[82:97]
	v_exp_f32_e32 v232, v154
	v_exp_f32_e32 v233, v155
	v_exp_f32_e32 v234, v152
	v_exp_f32_e32 v235, v153
	v_add_f32_e32 v146, v232, v146
	v_add_f32_e32 v146, v233, v146
	v_add_f32_e32 v146, v234, v146
	v_mfma_f32_32x32x16_bf16 v[66:81], v[236:239], v[98:101], v[66:81]
	v_exp_f32_e32 v236, v150
	v_exp_f32_e32 v237, v151
	v_exp_f32_e32 v238, v148
	v_exp_f32_e32 v239, v149
	v_add_f32_e32 v146, v235, v146
	v_add_f32_e32 v146, v236, v146
	v_add_f32_e32 v146, v237, v146
	v_add_f32_e32 v146, v238, v146
	v_add_f32_e32 v146, v239, v146
	v_add_f32_e32 v146, v240, v146
	v_add_f32_e32 v162, v241, v146
	v_mov_b32_e32 v163, v162
	s_nop 1
	v_permlane32_swap_b32_e32 v162, v163
	v_cvt_pk_bf16_f32 v146, v229, v231
	v_cvt_pk_bf16_f32 v147, v227, v230
	v_cvt_pk_bf16_f32 v148, v226, v228
	v_cvt_pk_bf16_f32 v149, v224, v225
	v_cvt_pk_bf16_f32 v150, v221, v223
	v_cvt_pk_bf16_f32 v151, v220, v222
	v_cvt_pk_bf16_f32 v152, v217, v219
	v_cvt_pk_bf16_f32 v153, v216, v218
	v_cvt_pk_bf16_f32 v154, v164, v165
	v_cvt_pk_bf16_f32 v155, v197, v215
	v_cvt_pk_bf16_f32 v156, v156, v157
	v_cvt_pk_bf16_f32 v157, v232, v233
	v_cvt_pk_bf16_f32 v216, v234, v235
	v_cvt_pk_bf16_f32 v217, v236, v237
	v_cvt_pk_bf16_f32 v218, v238, v239
	v_cvt_pk_bf16_f32 v219, v240, v241
	s_nop 0
	v_permlane32_swap_b32_e32 v146, v148
	v_permlane32_swap_b32_e32 v147, v149
	v_permlane32_swap_b32_e32 v150, v152
	v_permlane32_swap_b32_e32 v151, v153
	v_permlane32_swap_b32_e32 v154, v156
	v_permlane32_swap_b32_e32 v155, v157
	v_permlane32_swap_b32_e32 v216, v218
	v_permlane32_swap_b32_e32 v217, v219
	s_lshl_b32 s24, s17, 14
	v_add_u32_e32 v197, s24, v200
	ds_read_b64_tr_b16 v[228:229], v197 offset:0x2000
	ds_read_b64_tr_b16 v[230:231], v197 offset:0x2800
	ds_read_b64_tr_b16 v[232:233], v197 offset:0x3000
	ds_read_b64_tr_b16 v[234:235], v197 offset:0x3800
	s_nop 0
	v_mfma_f32_32x32x16_bf16 v[2:17], v[146:149], v[206:209], v[2:17]
	ds_read_b64_tr_b16 v[220:221], v197 offset:0x200
	ds_read_b64_tr_b16 v[222:223], v197 offset:0xa00
	v_max_f32_e32 v164, v83, v83
	v_max_f32_e32 v165, v82, v82
	v_max_f32_e32 v164, v165, v164
	v_max3_f32 v164, v164, v84, v85
	v_max3_f32 v164, v164, v86, v87
	v_mfma_f32_32x32x16_bf16 v[2:17], v[150:153], v[210:213], v[2:17]
	ds_read_b64_tr_b16 v[224:225], v197 offset:0x1200
	ds_read_b64_tr_b16 v[226:227], v197 offset:0x1a00
	v_max3_f32 v164, v164, v88, v89
	v_max3_f32 v164, v164, v90, v91
	v_max3_f32 v164, v164, v92, v93
	v_max3_f32 v164, v164, v94, v95
	v_max3_f32 v164, v164, v96, v97
	s_waitcnt lgkmcnt(6)
	v_mfma_f32_32x32x16_bf16 v[2:17], v[154:157], v[228:231], v[2:17]
	ds_read_b64_tr_b16 v[228:229], v197 offset:0x2200
	ds_read_b64_tr_b16 v[230:231], v197 offset:0x2a00
	ds_read_b64_tr_b16 v[236:237], v197 offset:0x3200
	ds_read_b64_tr_b16 v[238:239], v197 offset:0x3a00
	s_waitcnt lgkmcnt(8)
	v_mfma_f32_32x32x16_bf16 v[2:17], v[216:219], v[232:235], v[2:17]
	s_waitcnt lgkmcnt(6)
	v_mfma_f32_32x32x16_bf16 v[50:65], v[146:149], v[220:223], v[50:65]
	v_max3_f32 v164, v164, v66, v67
	v_max3_f32 v164, v164, v68, v69
	v_max3_f32 v164, v164, v70, v71
	v_max3_f32 v164, v164, v72, v73
	v_max3_f32 v164, v164, v74, v75
	v_max3_f32 v164, v164, v76, v77
	v_max3_f32 v164, v164, v78, v79
	s_waitcnt lgkmcnt(4)
	v_mfma_f32_32x32x16_bf16 v[50:65], v[150:153], v[224:227], v[50:65]
	v_max3_f32 v164, v164, v80, v81
	v_mov_b32_e32 v165, v164
	s_nop 1
	v_permlane32_swap_b32_e32 v164, v165
	ds_read_b64_tr_b16 v[220:221], v197 offset:0x400
	v_max_f32_e32 v165, v165, v165
	v_max_f32_e32 v164, v164, v164
	s_waitcnt lgkmcnt(3)
	v_mfma_f32_32x32x16_bf16 v[50:65], v[154:157], v[228:231], v[50:65]
	ds_read_b64_tr_b16 v[222:223], v197 offset:0xc00
	v_max_f32_e32 v164, v164, v165
	v_max_f32_e32 v165, v202, v202
	ds_read_b64_tr_b16 v[224:225], v197 offset:0x1400
	v_max_f32_e32 v165, v165, v164
	ds_read_b64_tr_b16 v[226:227], v197 offset:0x1c00
	v_sub_f32_e32 v215, v164, v202
	s_waitcnt lgkmcnt(4)
	v_mfma_f32_32x32x16_bf16 v[50:65], v[216:219], v[236:239], v[50:65]
	v_sub_f32_e32 v164, v202, v165
	ds_read_b64_tr_b16 v[228:229], v197 offset:0x2400
	v_mul_f32_e32 v164, 0x3dd53b94, v164
	ds_read_b64_tr_b16 v[230:231], v197 offset:0x2c00
	v_exp_f32_e32 v164, v164
	ds_read_b64_tr_b16 v[232:233], v197 offset:0x3400
	v_cmp_ge_f32_e32 vcc, s77, v215
	ds_read_b64_tr_b16 v[234:235], v197 offset:0x3c00
	s_cmp_eq_u64 vcc, exec
	s_cselect_b64 s[4:5], -1, 0
	v_cndmask_b32_e64 v164, v164, 1.0, s[4:5]
	s_waitcnt lgkmcnt(6)
	v_mfma_f32_32x32x16_bf16 v[34:49], v[146:149], v[220:223], v[34:49]
	ds_read_b64_tr_b16 v[220:221], v197 offset:0x600
	ds_read_b64_tr_b16 v[222:223], v197 offset:0xe00
	s_waitcnt lgkmcnt(6)
	v_mfma_f32_32x32x16_bf16 v[34:49], v[150:153], v[224:227], v[34:49]
	ds_read_b64_tr_b16 v[224:225], v197 offset:0x1600
	ds_read_b64_tr_b16 v[226:227], v197 offset:0x1e00
	s_waitcnt lgkmcnt(6)
	v_mfma_f32_32x32x16_bf16 v[34:49], v[154:157], v[228:231], v[34:49]
	ds_read_b64_tr_b16 v[228:229], v197 offset:0x2600
	ds_read_b64_tr_b16 v[230:231], v197 offset:0x2e00
	ds_read_b64_tr_b16 v[236:237], v197 offset:0x3600
	ds_read_b64_tr_b16 v[238:239], v197 offset:0x3e00
	s_waitcnt lgkmcnt(8)
	v_mfma_f32_32x32x16_bf16 v[34:49], v[216:219], v[232:235], v[34:49]
	s_waitcnt lgkmcnt(6)
	v_mfma_f32_32x32x16_bf16 v[18:33], v[146:149], v[220:223], v[18:33]
	v_cmp_gt_f32_e32 vcc, 1.0, v164
	s_waitcnt lgkmcnt(4)
	v_mfma_f32_32x32x16_bf16 v[18:33], v[150:153], v[224:227], v[18:33]
	s_waitcnt lgkmcnt(2)
	v_mfma_f32_32x32x16_bf16 v[18:33], v[154:157], v[228:231], v[18:33]
	s_waitcnt lgkmcnt(0)
	v_mfma_f32_32x32x16_bf16 v[18:33], v[216:219], v[236:239], v[18:33]
	s_cbranch_vccz .LBB0_547
	s_and_saveexec_b64 s[0:1], s[2:3]
	ds_write_b32 v170, v164 offset:128
	s_or_b64 exec, exec, s[0:1]
	s_waitcnt lgkmcnt(0)
	ds_read_b128 v[146:149], v158 offset:224
	ds_read_b128 v[150:153], v158 offset:192
	ds_read_b128 v[154:157], v158 offset:160
	ds_read_b128 v[216:219], v158 offset:128
	s_waitcnt lgkmcnt(0)
	v_pk_mul_f32 v[16:17], v[16:17], v[148:149]
	v_pk_mul_f32 v[12:13], v[12:13], v[152:153]
	v_pk_mul_f32 v[8:9], v[8:9], v[156:157]
	v_pk_mul_f32 v[4:5], v[4:5], v[218:219]
	v_pk_mul_f32 v[14:15], v[14:15], v[146:147]
	v_pk_mul_f32 v[10:11], v[10:11], v[150:151]
	v_pk_mul_f32 v[6:7], v[6:7], v[154:155]
	v_pk_mul_f32 v[2:3], v[2:3], v[216:217]
	v_pk_mul_f32 v[64:65], v[64:65], v[148:149]
	v_pk_mul_f32 v[60:61], v[60:61], v[152:153]
	v_pk_mul_f32 v[56:57], v[56:57], v[156:157]
	v_pk_mul_f32 v[52:53], v[52:53], v[218:219]
	v_pk_mul_f32 v[62:63], v[62:63], v[146:147]
	v_pk_mul_f32 v[58:59], v[58:59], v[150:151]
	v_pk_mul_f32 v[54:55], v[54:55], v[154:155]
	v_pk_mul_f32 v[50:51], v[50:51], v[216:217]
	v_pk_mul_f32 v[48:49], v[48:49], v[148:149]
	v_pk_mul_f32 v[44:45], v[44:45], v[152:153]
	v_pk_mul_f32 v[40:41], v[40:41], v[156:157]
	v_pk_mul_f32 v[36:37], v[36:37], v[218:219]
	v_pk_mul_f32 v[46:47], v[46:47], v[146:147]
	v_pk_mul_f32 v[42:43], v[42:43], v[150:151]
	v_pk_mul_f32 v[38:39], v[38:39], v[154:155]
	v_pk_mul_f32 v[34:35], v[34:35], v[216:217]
	v_pk_mul_f32 v[32:33], v[32:33], v[148:149]
	v_pk_mul_f32 v[28:29], v[28:29], v[152:153]
	v_pk_mul_f32 v[24:25], v[24:25], v[156:157]
	v_pk_mul_f32 v[20:21], v[20:21], v[218:219]
	v_pk_mul_f32 v[30:31], v[30:31], v[146:147]
	v_pk_mul_f32 v[26:27], v[26:27], v[150:151]
	v_pk_mul_f32 v[22:23], v[22:23], v[154:155]
	v_pk_mul_f32 v[18:19], v[18:19], v[216:217]
.LBB0_547:
	s_add_u32 s100, s38, s20
	s_addc_u32 s101, s39, s21
	s_add_u32 s100, s100, 0x149ec500
	s_addc_u32 s101, s101, 0
	s_lshl_b32 s99, s22, 14
	s_add_i32 s99, s89, s99
	s_mov_b32 m0, s99
	v_lshl_add_u64 v[254:255], v[248:249], 0, s[100:101]
	global_load_lds_dwordx4 v[254:255], off
	s_add_u32 s100, s100, 0x20000
	s_addc_u32 s101, s101, 0
	s_add_i32 m0, s99, 0x2000
	v_lshl_add_u64 v[254:255], v[248:249], 0, s[100:101]
	global_load_lds_dwordx4 v[254:255], off
	s_waitcnt vmcnt(2)
	s_add_i32 s0, s19, 1
	s_cmp_ge_u32 s0, s86
	s_cselect_b32 s98, 1, 0
	s_waitcnt vmcnt(2)
	s_barrier
.LBB0_549:
	v_cndmask_b32_e64 v165, v165, v202, s[4:5]
	v_mul_f32_e32 v154, 0xbdd53b94, v165
	v_fmamk_f32 v202, v69, 0x3dd53b94, v154
	v_fmamk_f32 v215, v70, 0x3dd53b94, v154
	v_fmamk_f32 v155, v66, 0x3dd53b94, v154
	v_fmamk_f32 v156, v67, 0x3dd53b94, v154
	v_fmamk_f32 v157, v68, 0x3dd53b94, v154
	v_fmamk_f32 v216, v71, 0x3dd53b94, v154
	v_fmamk_f32 v217, v72, 0x3dd53b94, v154
	v_fmamk_f32 v218, v73, 0x3dd53b94, v154
	ds_read_b128 v[66:69], v174 offset:32768
	ds_read_b128 v[70:73], v174 offset:40960
	ds_read_b128 v[146:149], v176 offset:32768
	ds_read_b128 v[150:153], v176 offset:40960
	s_cmp_lg_u32 s98, 0
	s_cbranch_scc1 .Lmla_nopf_stub
	s_add_u32 s0, s38, s20
	s_addc_u32 s1, s39, s21
	s_add_u32 s100, s0, s42
	s_addc_u32 s101, s1, s43
	s_mov_b32 m0, s93
	v_lshl_add_u64 v[254:255], v[246:247], 0, s[100:101]
	global_load_lds_dwordx4 v[254:255], off
	s_add_u32 s100, s0, s46
	s_addc_u32 s101, s1, s47
	s_mov_b32 m0, s94
	v_lshl_add_u64 v[254:255], v[246:247], 0, s[100:101]
	global_load_lds_dwordx4 v[254:255], off
	s_add_u32 s100, s38, s88
	s_addc_u32 s101, s39, s87
	s_add_u32 s100, s100, s58
	s_addc_u32 s101, s101, s59
	s_mov_b32 m0, s95
	v_lshl_add_u64 v[254:255], v[250:251], 0, s[100:101]
	global_load_lds_dwordx4 v[254:255], off

.LBB0_553:
	s_cmp_lg_u32 s98, 0
	s_cbranch_scc1 .Lmla_skipv
	s_add_u32 s100, s38, s20
	s_addc_u32 s101, s39, s21
	s_add_u32 s100, s100, s44
	s_addc_u32 s101, s101, s45
	s_add_i32 s99, s89, s24
	s_mov_b32 m0, s99
	v_lshl_add_u64 v[254:255], v[248:249], 0, s[100:101]
	global_load_lds_dwordx4 v[254:255], off
	s_add_u32 s100, s38, s20
	s_addc_u32 s101, s39, s21
	s_add_u32 s100, s100, s50
	s_addc_u32 s101, s101, s51
	s_add_i32 m0, s99, 0x2000
	v_lshl_add_u64 v[254:255], v[248:249], 0, s[100:101]
	global_load_lds_dwordx4 v[254:255], off
